# speedup vs baseline: 1.0194x; 1.0057x over previous
; #define PG8_STAGE(bufoff, gbase, voff) do { _Pragma("unroll") for (int _i = 0; _i < 2; ++_i) \
;         __builtin_amdgcn_global_load_lds((const unsigned*)((const char*)(gbase) + (voff)[_i]), (LAS unsigned*)(lds + (bufoff) + ldsw + _i * 8192), 16, 0, 0); } while (0)
; #define PG8_LDA(dst, b, h) do { _Pragma("unroll") for (int m = 0; m < 4; ++m) _Pragma("unroll") for (int k = 0; k < 2; ++k) dst[m][k] = *(const LAS bf16x8*)(lds + PG8_SA(b, h) + aoff + m * 2048 + k * 1024); } while (0)
; #define PG8_LDB(dst, b, h) do { _Pragma("unroll") for (int n = 0; n < 2; ++n) _Pragma("unroll") for (int k = 0; k < 2; ++k) dst[n][k] = *(const LAS bf16x8*)(lds + PG8_SB(b, h) + boff + n * 2048 + k * 1024); } while (0)
; #define PG8_WAIT_L(n) asm volatile("s_waitcnt lgkmcnt(" #n ")" ::: "memory")
; #define PG8_BAR __builtin_amdgcn_s_barrier()
; #define PG8_SCHED __builtin_amdgcn_sched_barrier(0)
; __device__ __forceinline__ void gemm_phase(LAS unsigned char* lds, const GemmD& g) {
;     ...
;     for (;;) {
;         const bool has_next = unit_get(g, nM, nN, G, cblk, ui + 1, nxt);
;         const char* nA = has_next ? (const char*)g.A + (size_t)nxt.pm * tstep + (size_t)nxt.k0 * kstep : cA; const char* nB = has_next ? (const char*)g.Bt + (size_t)nxt.pn * tstep + (size_t)nxt.k0 * kstep : cB;
;         const int nt = cur.nt;
;         for (int t = 0; t < nt; t += 2) {
;             const bool last = (t == nt - 2);
;             const char* a1 = cA + (size_t)(t + 1) * kstep;
;             const char* a2 = last ? nA : cA + (size_t)(t + 2) * kstep; const char* b2 = last ? nB : cB + (size_t)(t + 2) * kstep;
;             const char* a3 = a2 + kstep; const char* b3 = b2 + kstep;
;             PG8_LDB(B0, 0, 0); PG8_SCHED; PG8_LDA(At, 0, 0); PG8_STAGE(PG8_SA(1, 1), a1 + hstep, voffA);
;             PG8_WAIT_L(8); PG8_BAR; PG8_WAIT_L(0); PG8_MMA(0, 0, At, B0); PG8_BAR; PG8_SCHED;
;             PG8_LDB(B1, 0, 1); PG8_STAGE(PG8_SB(0, 0), b2, voffB);
;     ...
;         for (int a = 0; a < 2; ++a)
; #pragma unroll
;             for (int b = 0; b < 2; ++b)
; #pragma unroll
;                 for (int m = 0; m < 4; ++m)
; #pragma unroll
;                     for (int n = 0; n < 2; ++n) acc[a][b][m][n] = (f32x4){0.f, 0.f, 0.f, 0.f};
.LBB0_144:
	v_lshl_add_u64 v[132:133], v[2:3], 0, s[46:47]
	v_mov_b32_e32 v2, 0
	v_add_u32_e32 v135, -2, v134
	v_lshl_add_u64 v[130:131], v[4:5], 0, s[44:45]
	s_mov_b32 s4, 0
	v_mov_b32_e32 v3, v2
	v_mov_b32_e32 v4, v2
	v_mov_b32_e32 v5, v2
	v_mov_b32_e32 v6, v2
	v_mov_b32_e32 v7, v2
	v_mov_b32_e32 v8, v2
	v_mov_b32_e32 v9, v2
	v_mov_b32_e32 v18, v2
	v_mov_b32_e32 v19, v2
	v_mov_b32_e32 v20, v2
	v_mov_b32_e32 v21, v2
	v_mov_b32_e32 v22, v2
	v_mov_b32_e32 v23, v2
	v_mov_b32_e32 v24, v2
	v_mov_b32_e32 v25, v2
	v_mov_b32_e32 v34, v2
	v_mov_b32_e32 v35, v2
	v_mov_b32_e32 v36, v2
	v_mov_b32_e32 v37, v2
	v_mov_b32_e32 v38, v2
	v_mov_b32_e32 v39, v2
	v_mov_b32_e32 v40, v2
	v_mov_b32_e32 v41, v2
	v_mov_b32_e32 v50, v2
	v_mov_b32_e32 v51, v2
	v_mov_b32_e32 v52, v2
	v_mov_b32_e32 v53, v2
	v_mov_b32_e32 v54, v2
	v_mov_b32_e32 v55, v2
	v_mov_b32_e32 v56, v2
	v_mov_b32_e32 v57, v2
	v_mov_b32_e32 v10, v2
	v_mov_b32_e32 v11, v2
	v_mov_b32_e32 v12, v2
	v_mov_b32_e32 v13, v2
	v_mov_b32_e32 v14, v2
	v_mov_b32_e32 v15, v2
	v_mov_b32_e32 v16, v2
	v_mov_b32_e32 v17, v2
	v_mov_b32_e32 v26, v2
	v_mov_b32_e32 v27, v2
	v_mov_b32_e32 v28, v2
	v_mov_b32_e32 v29, v2
	v_mov_b32_e32 v30, v2
	v_mov_b32_e32 v31, v2
	v_mov_b32_e32 v32, v2
	v_mov_b32_e32 v33, v2
	v_mov_b32_e32 v42, v2
	v_mov_b32_e32 v43, v2
	v_mov_b32_e32 v44, v2
	v_mov_b32_e32 v45, v2
	v_mov_b32_e32 v46, v2
	v_mov_b32_e32 v47, v2
	v_mov_b32_e32 v48, v2
	v_mov_b32_e32 v49, v2
	v_mov_b32_e32 v58, v2
	v_mov_b32_e32 v59, v2
	v_mov_b32_e32 v60, v2
	v_mov_b32_e32 v61, v2
	v_mov_b32_e32 v62, v2
	v_mov_b32_e32 v63, v2
	v_mov_b32_e32 v64, v2
	v_mov_b32_e32 v65, v2
	v_mov_b32_e32 v66, v2
	v_mov_b32_e32 v67, v2
	v_mov_b32_e32 v68, v2
	v_mov_b32_e32 v69, v2
	v_mov_b32_e32 v70, v2
	v_mov_b32_e32 v71, v2
	v_mov_b32_e32 v72, v2
	v_mov_b32_e32 v73, v2
	s_waitcnt vmcnt(0)
	v_mov_b32_e32 v82, v2
	v_mov_b32_e32 v83, v2
	v_mov_b32_e32 v84, v2
	v_mov_b32_e32 v85, v2
	v_mov_b32_e32 v86, v2
	v_mov_b32_e32 v87, v2
	v_mov_b32_e32 v88, v2
	v_mov_b32_e32 v89, v2
	v_mov_b32_e32 v98, v2
	v_mov_b32_e32 v99, v2
	v_mov_b32_e32 v100, v2
	v_mov_b32_e32 v101, v2
	v_mov_b32_e32 v102, v2
	v_mov_b32_e32 v103, v2
	v_mov_b32_e32 v104, v2
	v_mov_b32_e32 v105, v2
	v_mov_b32_e32 v114, v2
	v_mov_b32_e32 v115, v2
	v_mov_b32_e32 v116, v2
	v_mov_b32_e32 v117, v2
	v_mov_b32_e32 v118, v2
	v_mov_b32_e32 v119, v2
	v_mov_b32_e32 v120, v2
	v_mov_b32_e32 v121, v2
	v_mov_b32_e32 v74, v2
	v_mov_b32_e32 v75, v2
	v_mov_b32_e32 v76, v2
	v_mov_b32_e32 v77, v2
	v_mov_b32_e32 v78, v2
	v_mov_b32_e32 v79, v2
	v_mov_b32_e32 v80, v2
	v_mov_b32_e32 v81, v2
	v_mov_b32_e32 v90, v2
	v_mov_b32_e32 v91, v2
	v_mov_b32_e32 v92, v2
	v_mov_b32_e32 v93, v2
	v_mov_b32_e32 v94, v2
	v_mov_b32_e32 v95, v2
	v_mov_b32_e32 v96, v2
	v_mov_b32_e32 v97, v2
	v_mov_b32_e32 v106, v2
	v_mov_b32_e32 v107, v2
	v_mov_b32_e32 v108, v2
	v_mov_b32_e32 v109, v2
	v_mov_b32_e32 v110, v2
	v_mov_b32_e32 v111, v2
	v_mov_b32_e32 v112, v2
	v_mov_b32_e32 v113, v2
	v_mov_b32_e32 v122, v2
	v_mov_b32_e32 v123, v2
	v_mov_b32_e32 v124, v2
	v_mov_b32_e32 v125, v2
	v_mov_b32_e32 v126, v2
	v_mov_b32_e32 v127, v2
	v_mov_b32_e32 v128, v2
	v_mov_b32_e32 v129, v2
	v_readfirstlane_b32 s98, v130
	v_readfirstlane_b32 s99, v131
	v_readfirstlane_b32 s100, v132
	v_readfirstlane_b32 s101, v133
	v_add_u32_e32 v242, s72, v172
	v_add_u32_e32 v243, s72, v168
	v_add_u32_e32 v244, 0x10000, v229
	v_add_u32_e32 v245, 0x14000, v229
	v_add_u32_e32 v246, 0x18000, v229
	v_add_u32_e32 v247, 0x1c000, v229
.LBB0_145:
	s_add_i32 s6, 0, 0x10000
	ds_read_b128 v[136:139], v244
	ds_read_b128 v[140:143], v244 offset:1024
	ds_read_b128 v[144:147], v244 offset:2048
	ds_read_b128 v[148:151], v244 offset:3072
	v_cmp_eq_u32_e32 vcc, s4, v135
	s_add_i32 s5, s4, 2
	s_add_i32 m0, s2, 0xc000
	ds_read_b128 v[152:155], v233
	ds_read_b128 v[156:159], v233 offset:1024
	ds_read_b128 v[160:163], v233 offset:2048
	ds_read_b128 v[184:187], v233 offset:3072
	ds_read_b128 v[188:191], v233 offset:4096
	ds_read_b128 v[192:195], v233 offset:5120
	ds_read_b128 v[196:199], v233 offset:6144
	ds_read_b128 v[200:203], v233 offset:7168
	global_load_lds_dwordx4 v174, s[98:99]
	s_add_i32 m0, s2, 0xe000
	s_nop 0
	global_load_lds_dwordx4 v176, s[98:99]
	s_cbranch_vccz .Lkl_notlast
	v_readfirstlane_b32 s98, v180
	v_readfirstlane_b32 s99, v181
	v_readfirstlane_b32 s100, v182
	v_readfirstlane_b32 s101, v183
	s_branch .Lkl_ptr_done

; #define PG8_STAGE(bufoff, gbase, voff) do { _Pragma("unroll") for (int _i = 0; _i < 2; ++_i) \
;         __builtin_amdgcn_global_load_lds((const unsigned*)((const char*)(gbase) + (voff)[_i]), (LAS unsigned*)(lds + (bufoff) + ldsw + _i * 8192), 16, 0, 0); } while (0)
; #define PG8_LDA(dst, b, h) do { _Pragma("unroll") for (int m = 0; m < 4; ++m) _Pragma("unroll") for (int k = 0; k < 2; ++k) dst[m][k] = *(const LAS bf16x8*)(lds + PG8_SA(b, h) + aoff + m * 2048 + k * 1024); } while (0)
; #define PG8_LDB(dst, b, h) do { _Pragma("unroll") for (int n = 0; n < 2; ++n) _Pragma("unroll") for (int k = 0; k < 2; ++k) dst[n][k] = *(const LAS bf16x8*)(lds + PG8_SB(b, h) + boff + n * 2048 + k * 1024); } while (0)
; #define PG8_MMA(ai, bj, At, Bt) do { __builtin_amdgcn_s_setprio(1); _Pragma("unroll") for (int m = 0; m < 4; ++m) _Pragma("unroll") for (int n = 0; n < 2; ++n) _Pragma("unroll") for (int k = 0; k < 2; ++k) \
;         acc[ai][bj][m][n] = __builtin_amdgcn_mfma_f32_16x16x32_bf16(Bt[n][k], At[m][k], acc[ai][bj][m][n], 0, 0, 0); __builtin_amdgcn_s_setprio(0); } while (0)
; #define PG8_WAIT_V(n) asm volatile("s_waitcnt vmcnt(" #n ")" ::: "memory")
; #define PG8_WAIT_L(n) asm volatile("s_waitcnt lgkmcnt(" #n ")" ::: "memory")
; #define PG8_BAR __builtin_amdgcn_s_barrier()
; #define PG8_SCHED __builtin_amdgcn_sched_barrier(0)
; __device__ __forceinline__ void gemm_phase(LAS unsigned char* lds, const GemmD& g) {
;     ...
;             PG8_WAIT_L(8); PG8_BAR; PG8_WAIT_L(0); PG8_MMA(0, 0, At, B0); PG8_BAR; PG8_SCHED;
;             PG8_LDB(B1, 0, 1); PG8_STAGE(PG8_SB(0, 0), b2, voffB);
;             PG8_BAR; PG8_WAIT_L(0); PG8_MMA(0, 1, At, B1); PG8_BAR;
;             PG8_LDA(At, 0, 1); PG8_STAGE(PG8_SA(0, 0), a2, voffA);
;             PG8_BAR; PG8_WAIT_L(0); PG8_MMA(1, 0, At, B0); PG8_BAR; PG8_SCHED;
;             PG8_STAGE(PG8_SB(0, 1), b2 + hstep, voffB);
;             PG8_WAIT_V(6); PG8_BAR; PG8_MMA(1, 1, At, B1); PG8_BAR;
;             PG8_LDB(B0, 1, 0); PG8_SCHED; PG8_LDA(At, 1, 0); PG8_STAGE(PG8_SA(0, 1), a2 + hstep, voffA);
.Lkl_ptr_done:
	s_waitcnt lgkmcnt(8)
	s_barrier
	s_waitcnt lgkmcnt(0)
	v_mfma_f32_16x16x32_bf16 v[126:129], v[136:139], v[152:155], v[126:129]
	v_mfma_f32_16x16x32_bf16 v[122:125], v[144:147], v[152:155], v[122:125]
	v_mfma_f32_16x16x32_bf16 v[110:113], v[136:139], v[160:163], v[110:113]
	v_mfma_f32_16x16x32_bf16 v[106:109], v[144:147], v[160:163], v[106:109]
	v_mfma_f32_16x16x32_bf16 v[94:97], v[136:139], v[188:191], v[94:97]
	v_mfma_f32_16x16x32_bf16 v[90:93], v[144:147], v[188:191], v[90:93]
	v_mfma_f32_16x16x32_bf16 v[78:81], v[136:139], v[196:199], v[78:81]
	v_mfma_f32_16x16x32_bf16 v[74:77], v[144:147], v[196:199], v[74:77]
	v_mfma_f32_16x16x32_bf16 v[126:129], v[140:143], v[156:159], v[126:129]
	v_mfma_f32_16x16x32_bf16 v[122:125], v[148:151], v[156:159], v[122:125]
	v_mfma_f32_16x16x32_bf16 v[110:113], v[140:143], v[184:187], v[110:113]
	v_mfma_f32_16x16x32_bf16 v[106:109], v[148:151], v[184:187], v[106:109]
	v_mfma_f32_16x16x32_bf16 v[94:97], v[140:143], v[192:195], v[94:97]
	v_mfma_f32_16x16x32_bf16 v[90:93], v[148:151], v[192:195], v[90:93]
	v_mfma_f32_16x16x32_bf16 v[78:81], v[140:143], v[200:203], v[78:81]
	v_mfma_f32_16x16x32_bf16 v[74:77], v[148:151], v[200:203], v[74:77]
	s_barrier
	s_add_i32 s4, 0, 0x14000
	s_add_i32 s6, s6, s87
	s_mov_b32 m0, s6
	ds_read_b128 v[204:207], v245
	ds_read_b128 v[208:211], v245 offset:1024
	ds_read_b128 v[234:237], v245 offset:2048
	ds_read_b128 v[238:241], v245 offset:3072
	global_load_lds_dwordx4 v172, s[100:101]
	s_add_i32 m0, s6, 0x2000
	s_nop 0
	global_load_lds_dwordx4 v168, s[100:101]
	s_barrier
	s_waitcnt lgkmcnt(0)
	v_mfma_f32_16x16x32_bf16 v[118:121], v[204:207], v[152:155], v[118:121]
	v_mfma_f32_16x16x32_bf16 v[114:117], v[234:237], v[152:155], v[114:117]
	v_mfma_f32_16x16x32_bf16 v[102:105], v[204:207], v[160:163], v[102:105]
	v_mfma_f32_16x16x32_bf16 v[98:101], v[234:237], v[160:163], v[98:101]
	v_mfma_f32_16x16x32_bf16 v[86:89], v[204:207], v[188:191], v[86:89]
	v_mfma_f32_16x16x32_bf16 v[82:85], v[234:237], v[188:191], v[82:85]
	v_mfma_f32_16x16x32_bf16 v[70:73], v[204:207], v[196:199], v[70:73]
	v_mfma_f32_16x16x32_bf16 v[66:69], v[234:237], v[196:199], v[66:69]
	v_mfma_f32_16x16x32_bf16 v[118:121], v[208:211], v[156:159], v[118:121]
	v_mfma_f32_16x16x32_bf16 v[114:117], v[238:241], v[156:159], v[114:117]
	v_mfma_f32_16x16x32_bf16 v[102:105], v[208:211], v[184:187], v[102:105]
	v_mfma_f32_16x16x32_bf16 v[98:101], v[238:241], v[184:187], v[98:101]
	v_mfma_f32_16x16x32_bf16 v[86:89], v[208:211], v[192:195], v[86:89]
	v_mfma_f32_16x16x32_bf16 v[82:85], v[238:241], v[192:195], v[82:85]
	v_mfma_f32_16x16x32_bf16 v[70:73], v[208:211], v[200:203], v[70:73]
	v_mfma_f32_16x16x32_bf16 v[66:69], v[238:241], v[200:203], v[66:69]
	s_barrier
	s_mov_b32 m0, s2
	ds_read_b128 v[152:155], v233 offset:16384
	ds_read_b128 v[156:159], v233 offset:17408
	ds_read_b128 v[160:163], v233 offset:18432
	ds_read_b128 v[184:187], v233 offset:19456
	ds_read_b128 v[188:191], v233 offset:20480
	ds_read_b128 v[192:195], v233 offset:21504
	ds_read_b128 v[196:199], v233 offset:22528
	ds_read_b128 v[200:203], v233 offset:23552
	global_load_lds_dwordx4 v170, s[98:99]
	s_mov_b32 m0, s3
	s_nop 0
	global_load_lds_dwordx4 v166, s[98:99]
	s_barrier
	s_waitcnt lgkmcnt(0)
	v_mfma_f32_16x16x32_bf16 v[62:65], v[136:139], v[152:155], v[62:65]
	v_mfma_f32_16x16x32_bf16 v[58:61], v[144:147], v[152:155], v[58:61]
	v_mfma_f32_16x16x32_bf16 v[46:49], v[136:139], v[160:163], v[46:49]
	v_mfma_f32_16x16x32_bf16 v[42:45], v[144:147], v[160:163], v[42:45]
	v_mfma_f32_16x16x32_bf16 v[30:33], v[136:139], v[188:191], v[30:33]
	v_mfma_f32_16x16x32_bf16 v[26:29], v[144:147], v[188:191], v[26:29]
	v_mfma_f32_16x16x32_bf16 v[14:17], v[136:139], v[196:199], v[14:17]
	v_mfma_f32_16x16x32_bf16 v[10:13], v[144:147], v[196:199], v[10:13]
	v_mfma_f32_16x16x32_bf16 v[62:65], v[140:143], v[156:159], v[62:65]
	v_mfma_f32_16x16x32_bf16 v[58:61], v[148:151], v[156:159], v[58:61]
	v_mfma_f32_16x16x32_bf16 v[46:49], v[140:143], v[184:187], v[46:49]
	v_mfma_f32_16x16x32_bf16 v[42:45], v[148:151], v[184:187], v[42:45]
	v_mfma_f32_16x16x32_bf16 v[30:33], v[140:143], v[192:195], v[30:33]
	v_mfma_f32_16x16x32_bf16 v[26:29], v[148:151], v[192:195], v[26:29]
	v_mfma_f32_16x16x32_bf16 v[14:17], v[140:143], v[200:203], v[14:17]
	v_mfma_f32_16x16x32_bf16 v[10:13], v[148:151], v[200:203], v[10:13]
	s_barrier
	s_add_i32 s4, s4, s87
	s_mov_b32 m0, s4
	s_nop 0
	global_load_lds_dwordx4 v242, s[100:101]
	s_add_i32 m0, s4, 0x2000
	s_nop 0
	global_load_lds_dwordx4 v243, s[100:101]
	s_waitcnt vmcnt(6)
	s_barrier
	v_mfma_f32_16x16x32_bf16 v[54:57], v[204:207], v[152:155], v[54:57]
	v_mfma_f32_16x16x32_bf16 v[50:53], v[234:237], v[152:155], v[50:53]
	v_mfma_f32_16x16x32_bf16 v[38:41], v[204:207], v[160:163], v[38:41]
	v_mfma_f32_16x16x32_bf16 v[34:37], v[234:237], v[160:163], v[34:37]
	v_mfma_f32_16x16x32_bf16 v[22:25], v[204:207], v[188:191], v[22:25]
	v_mfma_f32_16x16x32_bf16 v[18:21], v[234:237], v[188:191], v[18:21]
	v_mfma_f32_16x16x32_bf16 v[6:9], v[204:207], v[196:199], v[6:9]
	v_mfma_f32_16x16x32_bf16 v[2:5], v[234:237], v[196:199], v[2:5]
	v_mfma_f32_16x16x32_bf16 v[54:57], v[208:211], v[156:159], v[54:57]
	v_mfma_f32_16x16x32_bf16 v[50:53], v[238:241], v[156:159], v[50:53]
	v_mfma_f32_16x16x32_bf16 v[38:41], v[208:211], v[184:187], v[38:41]
	v_mfma_f32_16x16x32_bf16 v[34:37], v[238:241], v[184:187], v[34:37]
	v_mfma_f32_16x16x32_bf16 v[22:25], v[208:211], v[192:195], v[22:25]
	v_mfma_f32_16x16x32_bf16 v[18:21], v[238:241], v[192:195], v[18:21]
	v_mfma_f32_16x16x32_bf16 v[6:9], v[208:211], v[200:203], v[6:9]
	v_mfma_f32_16x16x32_bf16 v[2:5], v[238:241], v[200:203], v[2:5]
	s_barrier
; #define PG8_STAGE(bufoff, gbase, voff) do { _Pragma("unroll") for (int _i = 0; _i < 2; ++_i) \
;         __builtin_amdgcn_global_load_lds((const unsigned*)((const char*)(gbase) + (voff)[_i]), (LAS unsigned*)(lds + (bufoff) + ldsw + _i * 8192), 16, 0, 0); } while (0)
; #define PG8_LDA(dst, b, h) do { _Pragma("unroll") for (int m = 0; m < 4; ++m) _Pragma("unroll") for (int k = 0; k < 2; ++k) dst[m][k] = *(const LAS bf16x8*)(lds + PG8_SA(b, h) + aoff + m * 2048 + k * 1024); } while (0)
; #define PG8_LDB(dst, b, h) do { _Pragma("unroll") for (int n = 0; n < 2; ++n) _Pragma("unroll") for (int k = 0; k < 2; ++k) dst[n][k] = *(const LAS bf16x8*)(lds + PG8_SB(b, h) + boff + n * 2048 + k * 1024); } while (0)
; #define PG8_MMA(ai, bj, At, Bt) do { __builtin_amdgcn_s_setprio(1); _Pragma("unroll") for (int m = 0; m < 4; ++m) _Pragma("unroll") for (int n = 0; n < 2; ++n) _Pragma("unroll") for (int k = 0; k < 2; ++k) \
;         acc[ai][bj][m][n] = __builtin_amdgcn_mfma_f32_16x16x32_bf16(Bt[n][k], At[m][k], acc[ai][bj][m][n], 0, 0, 0); __builtin_amdgcn_s_setprio(0); } while (0)
; #define PG8_WAIT_V(n) asm volatile("s_waitcnt vmcnt(" #n ")" ::: "memory")
; #define PG8_WAIT_L(n) asm volatile("s_waitcnt lgkmcnt(" #n ")" ::: "memory")
; #define PG8_BAR __builtin_amdgcn_s_barrier()
; #define PG8_SCHED __builtin_amdgcn_sched_barrier(0)
; __device__ __forceinline__ void gemm_phase(LAS unsigned char* lds, const GemmD& g) {
;     ...
;             PG8_LDB(B0, 1, 0); PG8_SCHED; PG8_LDA(At, 1, 0); PG8_STAGE(PG8_SA(0, 1), a2 + hstep, voffA);
;             PG8_WAIT_L(8); PG8_BAR; PG8_WAIT_L(0); PG8_MMA(0, 0, At, B0); PG8_BAR; PG8_SCHED;
;             PG8_LDB(B1, 1, 1); PG8_STAGE(PG8_SB(1, 0), b3, voffB);
;             PG8_BAR; PG8_WAIT_L(0); PG8_MMA(0, 1, At, B1); PG8_BAR;
;             PG8_LDA(At, 1, 1); PG8_STAGE(PG8_SA(1, 0), a3, voffA);
;             PG8_BAR; PG8_WAIT_L(0); PG8_MMA(1, 0, At, B0); PG8_BAR; PG8_SCHED;
;             PG8_STAGE(PG8_SB(1, 1), b3 + hstep, voffB);
;             PG8_WAIT_V(6); PG8_BAR; PG8_MMA(1, 1, At, B1); PG8_BAR;
;         }
	s_add_i32 s4, 0, 0x18000
	ds_read_b128 v[136:139], v246
	ds_read_b128 v[140:143], v246 offset:1024
	ds_read_b128 v[144:147], v246 offset:2048
	ds_read_b128 v[148:151], v246 offset:3072
	s_mov_b32 m0, s64
	ds_read_b128 v[152:155], v233 offset:32768
	ds_read_b128 v[156:159], v233 offset:33792
	ds_read_b128 v[160:163], v233 offset:34816
	ds_read_b128 v[184:187], v233 offset:35840
	ds_read_b128 v[188:191], v233 offset:36864
	ds_read_b128 v[192:195], v233 offset:37888
	ds_read_b128 v[196:199], v233 offset:38912
	ds_read_b128 v[200:203], v233 offset:39936
	global_load_lds_dwordx4 v174, s[98:99]
	s_mov_b32 m0, s65
	s_nop 0
	global_load_lds_dwordx4 v176, s[98:99]
	s_waitcnt lgkmcnt(8)
	s_barrier
	s_waitcnt lgkmcnt(0)
	v_mfma_f32_16x16x32_bf16 v[126:129], v[136:139], v[152:155], v[126:129]
	v_mfma_f32_16x16x32_bf16 v[122:125], v[144:147], v[152:155], v[122:125]
	v_mfma_f32_16x16x32_bf16 v[110:113], v[136:139], v[160:163], v[110:113]
	v_mfma_f32_16x16x32_bf16 v[106:109], v[144:147], v[160:163], v[106:109]
	v_mfma_f32_16x16x32_bf16 v[94:97], v[136:139], v[188:191], v[94:97]
	v_mfma_f32_16x16x32_bf16 v[90:93], v[144:147], v[188:191], v[90:93]
	v_mfma_f32_16x16x32_bf16 v[78:81], v[136:139], v[196:199], v[78:81]
	v_mfma_f32_16x16x32_bf16 v[74:77], v[144:147], v[196:199], v[74:77]
	v_mfma_f32_16x16x32_bf16 v[126:129], v[140:143], v[156:159], v[126:129]
	v_mfma_f32_16x16x32_bf16 v[122:125], v[148:151], v[156:159], v[122:125]
	v_mfma_f32_16x16x32_bf16 v[110:113], v[140:143], v[184:187], v[110:113]
	v_mfma_f32_16x16x32_bf16 v[106:109], v[148:151], v[184:187], v[106:109]
	v_mfma_f32_16x16x32_bf16 v[94:97], v[140:143], v[192:195], v[94:97]
	v_mfma_f32_16x16x32_bf16 v[90:93], v[148:151], v[192:195], v[90:93]
	v_mfma_f32_16x16x32_bf16 v[78:81], v[140:143], v[200:203], v[78:81]
	v_mfma_f32_16x16x32_bf16 v[74:77], v[148:151], v[200:203], v[74:77]
	s_barrier
	s_add_i32 s6, 0, 0x1c000
	s_add_i32 s4, s4, s87
	ds_read_b128 v[204:207], v247
	ds_read_b128 v[208:211], v247 offset:1024
	ds_read_b128 v[234:237], v247 offset:2048
	ds_read_b128 v[238:241], v247 offset:3072
	s_add_u32 s100, s100, 0x80
	s_addc_u32 s101, s101, 0
	s_mov_b32 m0, s4
	s_nop 0
	global_load_lds_dwordx4 v172, s[100:101]
	s_add_i32 m0, s4, 0x2000
	s_nop 0
	global_load_lds_dwordx4 v168, s[100:101]
	s_barrier
	s_waitcnt lgkmcnt(0)
	v_mfma_f32_16x16x32_bf16 v[118:121], v[204:207], v[152:155], v[118:121]
	v_mfma_f32_16x16x32_bf16 v[114:117], v[234:237], v[152:155], v[114:117]
	v_mfma_f32_16x16x32_bf16 v[102:105], v[204:207], v[160:163], v[102:105]
	v_mfma_f32_16x16x32_bf16 v[98:101], v[234:237], v[160:163], v[98:101]
	v_mfma_f32_16x16x32_bf16 v[86:89], v[204:207], v[188:191], v[86:89]
	v_mfma_f32_16x16x32_bf16 v[82:85], v[234:237], v[188:191], v[82:85]
	v_mfma_f32_16x16x32_bf16 v[70:73], v[204:207], v[196:199], v[70:73]
	v_mfma_f32_16x16x32_bf16 v[66:69], v[234:237], v[196:199], v[66:69]
	v_mfma_f32_16x16x32_bf16 v[118:121], v[208:211], v[156:159], v[118:121]
	v_mfma_f32_16x16x32_bf16 v[114:117], v[238:241], v[156:159], v[114:117]
	v_mfma_f32_16x16x32_bf16 v[102:105], v[208:211], v[184:187], v[102:105]
	v_mfma_f32_16x16x32_bf16 v[98:101], v[238:241], v[184:187], v[98:101]
	v_mfma_f32_16x16x32_bf16 v[86:89], v[208:211], v[192:195], v[86:89]
	v_mfma_f32_16x16x32_bf16 v[82:85], v[238:241], v[192:195], v[82:85]
	v_mfma_f32_16x16x32_bf16 v[70:73], v[208:211], v[200:203], v[70:73]
	v_mfma_f32_16x16x32_bf16 v[66:69], v[238:241], v[200:203], v[66:69]
	s_barrier
	s_mov_b32 m0, s28
	s_add_u32 s98, s98, 0x80
	s_addc_u32 s99, s99, 0
	ds_read_b128 v[152:155], v233 offset:49152
	ds_read_b128 v[156:159], v233 offset:50176
	ds_read_b128 v[160:163], v233 offset:51200
	ds_read_b128 v[184:187], v233 offset:52224
	ds_read_b128 v[188:191], v233 offset:53248
	ds_read_b128 v[192:195], v233 offset:54272
	ds_read_b128 v[196:199], v233 offset:55296
	ds_read_b128 v[200:203], v233 offset:56320
	global_load_lds_dwordx4 v170, s[98:99]
	s_mov_b32 m0, s29
	s_nop 0
	global_load_lds_dwordx4 v166, s[98:99]
	s_barrier
	s_waitcnt lgkmcnt(0)
	v_mfma_f32_16x16x32_bf16 v[62:65], v[136:139], v[152:155], v[62:65]
	v_mfma_f32_16x16x32_bf16 v[58:61], v[144:147], v[152:155], v[58:61]
	v_mfma_f32_16x16x32_bf16 v[46:49], v[136:139], v[160:163], v[46:49]
	v_mfma_f32_16x16x32_bf16 v[42:45], v[144:147], v[160:163], v[42:45]
	v_mfma_f32_16x16x32_bf16 v[30:33], v[136:139], v[188:191], v[30:33]
	v_mfma_f32_16x16x32_bf16 v[26:29], v[144:147], v[188:191], v[26:29]
	v_mfma_f32_16x16x32_bf16 v[14:17], v[136:139], v[196:199], v[14:17]
	v_mfma_f32_16x16x32_bf16 v[10:13], v[144:147], v[196:199], v[10:13]
	v_mfma_f32_16x16x32_bf16 v[62:65], v[140:143], v[156:159], v[62:65]
	v_mfma_f32_16x16x32_bf16 v[58:61], v[148:151], v[156:159], v[58:61]
	v_mfma_f32_16x16x32_bf16 v[46:49], v[140:143], v[184:187], v[46:49]
	v_mfma_f32_16x16x32_bf16 v[42:45], v[148:151], v[184:187], v[42:45]
	v_mfma_f32_16x16x32_bf16 v[30:33], v[140:143], v[192:195], v[30:33]
	v_mfma_f32_16x16x32_bf16 v[26:29], v[148:151], v[192:195], v[26:29]
	v_mfma_f32_16x16x32_bf16 v[14:17], v[140:143], v[200:203], v[14:17]
	v_mfma_f32_16x16x32_bf16 v[10:13], v[148:151], v[200:203], v[10:13]
	s_barrier
	s_add_i32 s4, s6, s87
	s_mov_b32 m0, s4
	s_nop 0
	global_load_lds_dwordx4 v242, s[100:101]
	s_add_i32 m0, s4, 0x2000
	s_nop 0
	global_load_lds_dwordx4 v243, s[100:101]
	s_add_u32 s100, s100, 0x80
	s_addc_u32 s101, s101, 0
	s_mov_b32 s4, s5
	s_waitcnt vmcnt(6)
	s_barrier
	v_mfma_f32_16x16x32_bf16 v[54:57], v[204:207], v[152:155], v[54:57]
	v_mfma_f32_16x16x32_bf16 v[50:53], v[234:237], v[152:155], v[50:53]
	v_mfma_f32_16x16x32_bf16 v[38:41], v[204:207], v[160:163], v[38:41]
	v_mfma_f32_16x16x32_bf16 v[34:37], v[234:237], v[160:163], v[34:37]
	v_mfma_f32_16x16x32_bf16 v[22:25], v[204:207], v[188:191], v[22:25]
	v_mfma_f32_16x16x32_bf16 v[18:21], v[234:237], v[188:191], v[18:21]
	v_mfma_f32_16x16x32_bf16 v[6:9], v[204:207], v[196:199], v[6:9]
	v_mfma_f32_16x16x32_bf16 v[2:5], v[234:237], v[196:199], v[2:5]
	v_mfma_f32_16x16x32_bf16 v[54:57], v[208:211], v[156:159], v[54:57]
	v_mfma_f32_16x16x32_bf16 v[50:53], v[238:241], v[156:159], v[50:53]
	v_mfma_f32_16x16x32_bf16 v[38:41], v[208:211], v[184:187], v[38:41]
	v_mfma_f32_16x16x32_bf16 v[34:37], v[238:241], v[184:187], v[34:37]
	v_mfma_f32_16x16x32_bf16 v[22:25], v[208:211], v[192:195], v[22:25]
	v_mfma_f32_16x16x32_bf16 v[18:21], v[238:241], v[192:195], v[18:21]
	v_mfma_f32_16x16x32_bf16 v[6:9], v[208:211], v[200:203], v[6:9]
	v_mfma_f32_16x16x32_bf16 v[2:5], v[238:241], v[200:203], v[2:5]
	s_barrier
	s_cbranch_vccz .LBB0_145
	v_lshl_add_u32 v184, s56, 8, v228
	s_cmp_lt_i32 s66, 0
	s_mov_b64 s[4:5], -1
	s_cbranch_scc0 .LBB0_704
